# P0 W_in transposition: second item's loads issued before the first item is transposed (two-item waves)
# speedup vs baseline: 1.0015x; 1.0015x over previous
; __host__ __device__ __forceinline__ void tile_hp(int q, int bj, int& h, int& part) { if (q < 4) { h = q; part = bj; } else if (q < 6) { h = 2 * (q - 4) + bj; part = 2; } else { h = 2 * (q - 6) + bj; part = 3; } }
; __host__ __device__ __forceinline__ int tile_slot(int pn) { if (pn >= 16) return pn - 12; const int q = pn & 7; if (q >= 6) return (pn >> 3) * 2 + (q - 6); return (pn >> 3) * 6 + q; }
; #define LAS __attribute__((address_space(3)))
; __device__ __forceinline__ unsigned long long rt() { return __builtin_amdgcn_s_memrealtime(); }
; __host__ __device__ __forceinline__ int orig_col(int n) {
;     if (n >= 4096) { const int m = n - 4096; return 4104 + ((m >> 7) & 1) * 1024 + (m >> 8) * 128 + (m & 127); }
;     const int grp = n >> 11, q = (n >> 8) & 7, bj = (n >> 7) & 1, c = n & 127; int h, part; tile_hp(q, bj, h, part);
;     if (grp == 0) return part * 512 + h * 128 + c;
;     return (part < 3 ? 2048 + part * 512 : 3584) + h * 128 + c;
; }
; __global__ void __launch_bounds__(NWAVES * 64, 2) fwd(Args args) {
;     ...
;     if (IN(0)) {
;         const unsigned long long amp_t0_0 = (PROBE_AMP == 0) ? rt() : 0ull;
;         _Pragma("unroll 1") for (int rep_ = 0; rep_ < ((PROBE == 0) ? 2 : 1); ++rep_) {
;         const int gw = vcu * NWAVES + wave, NGW = G * NWAVES;
;         LAS float* scr = (LAS float*)(lds + RING_OFF + wave * 8704);
;         constexpr int I_IN = 16 * 192;
;         for (int it = gw; it < I_IN; it += NGW) { const int kb = it / 192, nb = it % 192, pn = nb >> 3, row = tile_slot(pn) * 256 + (nb & 7) * 32;
;             p0_transpose_item(w_in, PROJW, orig_col(32 * nb), 64 * kb, tile_is_late(pn) ? WING_T : WIN_T, 1024, row, 0, scr, lane); }
.LBB0_17:
	s_or_b64 exec, exec, s[6:7]
	s_add_u32 s84, s60, 0x600000
	s_addc_u32 s5, s61, 0
	s_add_u32 s64, s60, 0xc00000
	s_addc_u32 s65, s61, 0
	s_lshr_b32 s48, s66, 6
	s_load_dwordx16 s[16:31], s[0:1], 0x0
	s_cmp_lt_i32 s56, 1
	s_cselect_b64 s[6:7], -1, 0
	s_cmp_gt_i32 s57, 0
	s_cselect_b64 s[10:11], -1, 0
	s_and_b64 s[6:7], s[6:7], s[10:11]
	s_andn2_b64 vcc, exec, s[6:7]
	v_and_b32_e32 v234, 63, v0
	v_writelane_b32 v240, s48, 2
	s_cbranch_vccnz .LBB0_123
	s_lshl_b32 s3, s8, 3
	s_add_i32 s40, s3, s48
	s_lshl_b32 s42, s34, 3
	v_lshrrev_b32_e32 v8, 3, v234
	s_cmpk_gt_i32 s40, 0xbff
	v_lshlrev_b32_e32 v9, 3, v0
	v_mov_b32_e32 v3, 0
	v_lshlrev_b32_e32 v34, 2, v8
	s_cbranch_scc1 .LBB0_43
	s_mul_i32 s3, s48, 0x2200
	v_lshlrev_b32_e32 v1, 4, v0
	s_add_i32 s3, s3, 0
	v_and_b32_e32 v2, 0x70, v1
	s_waitcnt lgkmcnt(0)
	v_lshl_add_u64 v[4:5], s[20:21], 0, v[2:3]
	v_add_u32_e32 v15, s3, v2
	v_mul_u32_u24_e32 v16, 0x84, v8
	v_and_b32_e32 v2, 56, v9
	v_mul_u32_u24_e32 v14, 0x84, v2
	v_add_u32_e32 v15, v15, v16
	v_or_b32_e32 v1, 8, v8
	v_or_b32_e32 v6, 16, v8
	v_or_b32_e32 v7, 24, v8
	v_or_b32_e32 v10, 32, v8
	v_or_b32_e32 v11, 40, v8
	v_or_b32_e32 v12, 48, v8
	v_or_b32_e32 v13, 56, v8
	v_add3_u32 v14, s3, v14, v34
	s_lshl_b32 s3, s40, 5
	s_lshl_b32 s4, s42, 5
	s_lshl_b32 s12, s40, 8
	s_lshl_b32 s13, s42, 8
	s_movk_i32 s14, 0x6020
	v_add_u32_e32 v16, 0x420, v15
	v_add_u32_e32 v17, 0x428, v15
	v_add_u32_e32 v18, 0x840, v15
	v_add_u32_e32 v19, 0x848, v15
	v_add_u32_e32 v20, 0xc60, v15
	v_add_u32_e32 v21, 0xc68, v15
	v_add_u32_e32 v22, 0x1080, v15
	v_add_u32_e32 v23, 0x1088, v15
	v_add_u32_e32 v24, 0x14a0, v15
	v_add_u32_e32 v25, 0x14a8, v15
	v_add_u32_e32 v26, 0x18c0, v15
	v_add_u32_e32 v27, 0x18c8, v15
	v_add_u32_e32 v28, 0x1ce0, v15
	v_add_u32_e32 v29, 0x1ce8, v15
	v_lshlrev_b32_e32 v2, 1, v2
	s_mov_b32 s15, s40
	s_branch .LBB0_21
.LBB0_21:
	s_mul_hi_i32 s6, s15, 0x2aaaaaab
	s_lshr_b32 s7, s6, 31
	s_ashr_i32 s11, s6, 5
	s_add_i32 s11, s11, s7
	s_mul_i32 s6, s11, 0xffffff40
	s_add_i32 s33, s15, s6
	s_ashr_i32 s10, s33, 3
	s_cmp_gt_i32 s10, 15
	s_cselect_b64 s[6:7], -1, 0
	s_cmp_lt_i32 s10, 16
	s_mov_b64 s[8:9], -1
	s_cbranch_scc0 .LBB0_27
	s_bfe_u32 s36, s33, 0x30003
	s_cmp_lt_u32 s36, 6
	s_cbranch_scc0 .LBB0_24
	s_ashr_i32 s8, s33, 6
	s_mul_i32 s8, s8, 6
	s_add_i32 s35, s8, s36
	s_mov_b64 s[8:9], 0

; __host__ __device__ __forceinline__ int tile_slot(int pn) { if (pn >= 16) return pn - 12; const int q = pn & 7; if (q >= 6) return (pn >> 3) * 2 + (q - 6); return (pn >> 3) * 6 + q; }
; #define GAS __attribute__((address_space(1)))
; #define LAS __attribute__((address_space(3)))
; __device__ __forceinline__ void p0_transpose_item(const float* W, int ldw, int src_col0, int k0, bf16_t* WT, int ldk, int dst_row0, int dst_k0, LAS float* scr, int lane) {
; #pragma unroll
;     for (int i = 0; i < 8; ++i) { const int kk = 8 * i + (lane >> 3), n4 = 4 * (lane & 7);
;         const f32x4 w = *(const GAS f32x4*)(W + (size_t)(k0 + kk) * ldw + src_col0 + n4); LAS float* d = scr + kk * 33 + n4; d[0] = w[0]; d[1] = w[1]; d[2] = w[2]; d[3] = w[3]; }
; __global__ void __launch_bounds__(NWAVES * 64, 2) fwd(Args args) {
;     ...
;         for (int it = gw; it < I_IN; it += NGW) { const int kb = it / 192, nb = it % 192, pn = nb >> 3, row = tile_slot(pn) * 256 + (nb & 7) * 32;
;             p0_transpose_item(w_in, PROJW, orig_col(32 * nb), 64 * kb, tile_is_late(pn) ? WING_T : WIN_T, 1024, row, 0, scr, lane); }
.LBB0_20:
	s_lshl_b32 s8, s35, 8
	s_and_b32 s9, s36, 0xe0
	s_or_b32 s35, s8, s9
	s_lshl_b32 s8, s11, 6
	s_and_b32 s9, s33, 48
	s_cmp_eq_u32 s9, 48
	s_cselect_b64 s[36:37], -1, 0
	s_or_b64 s[6:7], s[6:7], s[36:37]
	s_and_b64 s[6:7], s[6:7], exec
	s_cselect_b32 s33, s5, s65
	s_cselect_b32 s36, s84, s64
	s_ashr_i32 s11, s10, 31
	v_lshl_add_u64 v[60:61], s[10:11], 2, v[4:5]
	v_or_b32_e32 v35, s8, v6
	v_mad_i64_i32 v[40:41], s[6:7], v35, s14, v[60:61]
	v_or_b32_e32 v35, s8, v7
	v_mad_i64_i32 v[44:45], s[6:7], v35, s14, v[60:61]
	v_or_b32_e32 v35, s8, v10
	v_or_b32_e32 v30, s8, v8
	v_or_b32_e32 v32, s8, v1
	v_mad_i64_i32 v[48:49], s[6:7], v35, s14, v[60:61]
	v_or_b32_e32 v35, s8, v11
	v_mad_i64_i32 v[30:31], s[6:7], v30, s14, v[60:61]
	v_mad_i64_i32 v[36:37], s[6:7], v32, s14, v[60:61]
	v_mad_i64_i32 v[52:53], s[6:7], v35, s14, v[60:61]
	global_load_dwordx4 v[30:33], v[30:31], off nt
	s_nop 0
	global_load_dwordx4 v[36:39], v[36:37], off nt
	s_nop 0
	global_load_dwordx4 v[40:43], v[40:41], off nt
	s_nop 0
	global_load_dwordx4 v[44:47], v[44:45], off nt
	s_nop 0
	global_load_dwordx4 v[48:51], v[48:49], off nt
	s_nop 0
	global_load_dwordx4 v[52:55], v[52:53], off nt
	v_or_b32_e32 v35, s8, v12
	v_mad_i64_i32 v[56:57], s[6:7], v35, s14, v[60:61]
	global_load_dwordx4 v[56:59], v[56:57], off nt
	v_or_b32_e32 v35, s8, v13
	v_mad_i64_i32 v[60:61], s[6:7], v35, s14, v[60:61]
	global_load_dwordx4 v[60:63], v[60:61], off nt
	s_ashr_i32 s9, s8, 31
	s_lshl_b64 s[6:7], s[8:9], 1
	v_or_b32_e32 v64, s35, v8
	s_add_u32 s6, s36, s6
	v_ashrrev_i32_e32 v65, 31, v64
	s_addc_u32 s7, s33, s7
	v_lshlrev_b64 v[64:65], 11, v[64:65]
	v_lshl_add_u64 v[68:69], s[6:7], 0, v[2:3]
	v_or_b32_e32 v66, s35, v1
	v_lshl_add_u64 v[64:65], v[68:69], 0, v[64:65]
	v_ashrrev_i32_e32 v67, 31, v66
	v_lshlrev_b64 v[66:67], 11, v[66:67]
	v_lshl_add_u64 v[66:67], v[68:69], 0, v[66:67]
	s_add_i32 s15, s15, s42
	s_add_i32 s3, s3, s4
	s_add_i32 s12, s12, s13
	s_cmpk_gt_i32 s15, 0xbff
	s_cbranch_scc1 .Lw0_single
	s_mul_hi_i32 s6, s15, 0x2aaaaaab
	s_lshr_b32 s7, s6, 31
	s_ashr_i32 s11, s6, 5
	s_add_i32 s11, s11, s7
	s_mul_i32 s6, s11, 0xffffff40
	s_add_i32 s33, s15, s6
	s_ashr_i32 s10, s33, 3
	s_cmp_gt_i32 s10, 15
	s_cselect_b64 s[6:7], -1, 0
	s_cmp_lt_i32 s10, 16
	s_mov_b64 s[8:9], -1
	s_cbranch_scc0 .Lw0c_27
	s_bfe_u32 s36, s33, 0x30003
	s_cmp_lt_u32 s36, 6
	s_cbranch_scc0 .Lw0c_24
	s_ashr_i32 s8, s33, 6
	s_mul_i32 s8, s8, 6
	s_add_i32 s100, s8, s36
	s_mov_b64 s[8:9], 0
.Lw0c_24:
	s_andn2_b64 vcc, exec, s[8:9]
	s_cbranch_vccnz .Lw0c_26
	s_ashr_i32 s8, s33, 5
	s_and_b32 s8, s8, -2
	s_add_i32 s8, s36, s8
	s_add_i32 s100, s8, -6

.Lw0c_27:
	s_andn2_b64 vcc, exec, s[8:9]
	s_cbranch_vccnz .Lw0c_29
	s_add_i32 s100, s10, -12

; #define GAS __attribute__((address_space(1)))
; #define LAS __attribute__((address_space(3)))
; #define LDS_WAIT() asm volatile("s_waitcnt lgkmcnt(0)" ::: "memory")
; __device__ __forceinline__ unsigned pk2(float lo, float hi) { const f32x2_t v = {lo, hi}; return __builtin_bit_cast(unsigned, __builtin_convertvector(v, bf16x2_t)); }
; __device__ __forceinline__ void p0_transpose_item(const float* W, int ldw, int src_col0, int k0, bf16_t* WT, int ldk, int dst_row0, int dst_k0, LAS float* scr, int lane) {
; #pragma unroll
;     for (int i = 0; i < 8; ++i) { const int kk = 8 * i + (lane >> 3), n4 = 4 * (lane & 7);
;         const f32x4 w = *(const GAS f32x4*)(W + (size_t)(k0 + kk) * ldw + src_col0 + n4); LAS float* d = scr + kk * 33 + n4; d[0] = w[0]; d[1] = w[1]; d[2] = w[2]; d[3] = w[3]; }
;     LDS_WAIT(); asm volatile("" ::: "memory");
;     const int c = lane & 7;
; #pragma unroll
;     for (int j = 0; j < 4; ++j) { const int n = (lane >> 3) + 8 * j; const LAS float* s = scr + (8 * c) * 33 + n;
;         v4u o; o.x = pk2(s[0 * 33], s[1 * 33]); o.y = pk2(s[2 * 33], s[3 * 33]); o.z = pk2(s[4 * 33], s[5 * 33]); o.w = pk2(s[6 * 33], s[7 * 33]);
;         *(GAS v4u*)(WT + (size_t)(dst_row0 + n) * ldk + dst_k0 + k0 + 8 * c) = o; }
;     LDS_WAIT(); asm volatile("" ::: "memory");
; }
.Lw0_L2:
	s_lshl_b32 s8, s100, 8
	s_and_b32 s9, s36, 0xe0
	s_or_b32 s100, s8, s9
	s_lshl_b32 s8, s11, 6
	s_and_b32 s9, s33, 48
	s_cmp_eq_u32 s9, 48
	s_cselect_b64 s[36:37], -1, 0
	s_or_b64 s[6:7], s[6:7], s[36:37]
	s_and_b64 s[6:7], s[6:7], exec
	s_cselect_b32 s33, s5, s65
	s_cselect_b32 s36, s84, s64
	s_ashr_i32 s11, s10, 31
	v_lshl_add_u64 v[100:101], s[10:11], 2, v[4:5]
	v_or_b32_e32 v75, s8, v6
	v_mad_i64_i32 v[80:81], s[6:7], v75, s14, v[100:101]
	v_or_b32_e32 v75, s8, v7
	v_mad_i64_i32 v[84:85], s[6:7], v75, s14, v[100:101]
	v_or_b32_e32 v75, s8, v10
	v_or_b32_e32 v70, s8, v8
	v_or_b32_e32 v72, s8, v1
	v_mad_i64_i32 v[88:89], s[6:7], v75, s14, v[100:101]
	v_or_b32_e32 v75, s8, v11
	v_mad_i64_i32 v[70:71], s[6:7], v70, s14, v[100:101]
	v_mad_i64_i32 v[76:77], s[6:7], v72, s14, v[100:101]
	v_mad_i64_i32 v[92:93], s[6:7], v75, s14, v[100:101]
	global_load_dwordx4 v[70:73], v[70:71], off nt
	s_nop 0
	global_load_dwordx4 v[76:79], v[76:77], off nt
	s_nop 0
	global_load_dwordx4 v[80:83], v[80:81], off nt
	s_nop 0
	global_load_dwordx4 v[84:87], v[84:85], off nt
	s_nop 0
	global_load_dwordx4 v[88:91], v[88:89], off nt
	s_nop 0
	global_load_dwordx4 v[92:95], v[92:93], off nt
	v_or_b32_e32 v75, s8, v12
	v_mad_i64_i32 v[96:97], s[6:7], v75, s14, v[100:101]
	global_load_dwordx4 v[96:99], v[96:97], off nt
	v_or_b32_e32 v75, s8, v13
	v_mad_i64_i32 v[100:101], s[6:7], v75, s14, v[100:101]
	global_load_dwordx4 v[100:103], v[100:101], off nt
	s_ashr_i32 s9, s8, 31
	s_lshl_b64 s[6:7], s[8:9], 1
	v_or_b32_e32 v104, s100, v8
	s_add_u32 s6, s36, s6
	v_ashrrev_i32_e32 v105, 31, v104
	s_addc_u32 s7, s33, s7
	v_lshlrev_b64 v[104:105], 11, v[104:105]
	v_lshl_add_u64 v[108:109], s[6:7], 0, v[2:3]
	v_or_b32_e32 v106, s100, v1
	v_lshl_add_u64 v[104:105], v[108:109], 0, v[104:105]
	v_ashrrev_i32_e32 v107, 31, v106
	v_lshlrev_b64 v[106:107], 11, v[106:107]
	v_lshl_add_u64 v[106:107], v[108:109], 0, v[106:107]
	s_waitcnt vmcnt(15)
	ds_write2_b32 v15, v30, v31 offset1:1
	ds_write2_b32 v15, v32, v33 offset0:2 offset1:3
	s_waitcnt vmcnt(14)
	ds_write2_b32 v16, v36, v37 offset1:1
	ds_write2_b32 v17, v38, v39 offset1:1
	s_waitcnt vmcnt(13)
	ds_write2_b32 v18, v40, v41 offset1:1
	ds_write2_b32 v19, v42, v43 offset1:1
	s_waitcnt vmcnt(12)
	ds_write2_b32 v20, v44, v45 offset1:1
	ds_write2_b32 v21, v46, v47 offset1:1
	s_waitcnt vmcnt(11)
	ds_write2_b32 v22, v48, v49 offset1:1
	ds_write2_b32 v23, v50, v51 offset1:1
	s_waitcnt vmcnt(10)
	ds_write2_b32 v24, v52, v53 offset1:1
	ds_write2_b32 v25, v54, v55 offset1:1
	s_waitcnt vmcnt(9)
	ds_write2_b32 v26, v56, v57 offset1:1
	ds_write2_b32 v27, v58, v59 offset1:1
	s_waitcnt vmcnt(8)
	ds_write2_b32 v28, v60, v61 offset1:1
	ds_write2_b32 v29, v62, v63 offset1:1
	s_waitcnt lgkmcnt(0)
	ds_read2_b32 v[32:33], v14 offset0:33 offset1:41
	ds_read2_b32 v[36:37], v14 offset1:8
	ds_read2_b32 v[38:39], v14 offset0:66 offset1:74
	ds_read2_b32 v[40:41], v14 offset0:99 offset1:107
	ds_read2_b32 v[42:43], v14 offset0:132 offset1:140
	ds_read2_b32 v[44:45], v14 offset0:165 offset1:173
	ds_read2_b32 v[46:47], v14 offset0:198 offset1:206
	ds_read2_b32 v[48:49], v14 offset0:231 offset1:239
	ds_read2_b32 v[50:51], v14 offset0:49 offset1:57
	ds_read2_b32 v[52:53], v14 offset0:16 offset1:24
	ds_read2_b32 v[54:55], v14 offset0:82 offset1:90
	ds_read2_b32 v[56:57], v14 offset0:115 offset1:123
	ds_read2_b32 v[58:59], v14 offset0:148 offset1:156
	ds_read2_b32 v[60:61], v14 offset0:181 offset1:189
	s_waitcnt lgkmcnt(12)
	v_cvt_pk_bf16_f32 v30, v36, v32
	s_waitcnt lgkmcnt(10)
	v_cvt_pk_bf16_f32 v31, v38, v40
	v_cvt_pk_bf16_f32 v36, v37, v33
	s_waitcnt lgkmcnt(8)
	v_cvt_pk_bf16_f32 v32, v42, v44
	s_waitcnt lgkmcnt(6)
	v_cvt_pk_bf16_f32 v33, v46, v48
	global_store_dwordx4 v[64:65], v[30:33], off sc1
	v_cvt_pk_bf16_f32 v37, v39, v41
	v_cvt_pk_bf16_f32 v38, v43, v45
	ds_read2_b32 v[40:41], v14 offset0:214 offset1:222
	ds_read2_b32 v[42:43], v14 offset0:247 offset1:255
	v_cvt_pk_bf16_f32 v39, v47, v49
	global_store_dwordx4 v[66:67], v[36:39], off sc1
	s_waitcnt lgkmcnt(6)
	v_cvt_pk_bf16_f32 v30, v52, v50
	s_waitcnt lgkmcnt(4)
	v_cvt_pk_bf16_f32 v31, v54, v56
	v_or_b32_e32 v36, s35, v6
	v_ashrrev_i32_e32 v37, 31, v36
	v_lshlrev_b64 v[36:37], 11, v[36:37]
	s_waitcnt lgkmcnt(2)
	v_cvt_pk_bf16_f32 v32, v58, v60
	s_waitcnt lgkmcnt(0)
	v_cvt_pk_bf16_f32 v33, v40, v42
	v_lshl_add_u64 v[36:37], v[68:69], 0, v[36:37]
	global_store_dwordx4 v[36:37], v[30:33], off sc1
	v_or_b32_e32 v36, s35, v7
	v_ashrrev_i32_e32 v37, 31, v36
	v_lshlrev_b64 v[36:37], 11, v[36:37]
	v_cvt_pk_bf16_f32 v30, v53, v51
	v_cvt_pk_bf16_f32 v31, v55, v57
	v_cvt_pk_bf16_f32 v32, v59, v61
	v_cvt_pk_bf16_f32 v33, v41, v43
	v_lshl_add_u64 v[36:37], v[68:69], 0, v[36:37]
	global_store_dwordx4 v[36:37], v[30:33], off sc1
	s_waitcnt lgkmcnt(0)
	s_waitcnt vmcnt(7)
	ds_write2_b32 v15, v70, v71 offset1:1
	ds_write2_b32 v15, v72, v73 offset0:2 offset1:3
	s_waitcnt vmcnt(6)
	ds_write2_b32 v16, v76, v77 offset1:1
	ds_write2_b32 v17, v78, v79 offset1:1
	s_waitcnt vmcnt(5)
	ds_write2_b32 v18, v80, v81 offset1:1
	ds_write2_b32 v19, v82, v83 offset1:1
	s_waitcnt vmcnt(4)
	ds_write2_b32 v20, v84, v85 offset1:1
	ds_write2_b32 v21, v86, v87 offset1:1
	s_waitcnt vmcnt(3)
	ds_write2_b32 v22, v88, v89 offset1:1
	ds_write2_b32 v23, v90, v91 offset1:1
	s_waitcnt vmcnt(2)
; #define GAS __attribute__((address_space(1)))
; #define LAS __attribute__((address_space(3)))
; #define LDS_WAIT() asm volatile("s_waitcnt lgkmcnt(0)" ::: "memory")
; __device__ __forceinline__ unsigned pk2(float lo, float hi) { const f32x2_t v = {lo, hi}; return __builtin_bit_cast(unsigned, __builtin_convertvector(v, bf16x2_t)); }
; __device__ __forceinline__ void p0_transpose_item(const float* W, int ldw, int src_col0, int k0, bf16_t* WT, int ldk, int dst_row0, int dst_k0, LAS float* scr, int lane) {
; #pragma unroll
;     for (int i = 0; i < 8; ++i) { const int kk = 8 * i + (lane >> 3), n4 = 4 * (lane & 7);
;         const f32x4 w = *(const GAS f32x4*)(W + (size_t)(k0 + kk) * ldw + src_col0 + n4); LAS float* d = scr + kk * 33 + n4; d[0] = w[0]; d[1] = w[1]; d[2] = w[2]; d[3] = w[3]; }
;     LDS_WAIT(); asm volatile("" ::: "memory");
;     const int c = lane & 7;
; #pragma unroll
;     for (int j = 0; j < 4; ++j) { const int n = (lane >> 3) + 8 * j; const LAS float* s = scr + (8 * c) * 33 + n;
;         v4u o; o.x = pk2(s[0 * 33], s[1 * 33]); o.y = pk2(s[2 * 33], s[3 * 33]); o.z = pk2(s[4 * 33], s[5 * 33]); o.w = pk2(s[6 * 33], s[7 * 33]);
;         *(GAS v4u*)(WT + (size_t)(dst_row0 + n) * ldk + dst_k0 + k0 + 8 * c) = o; }
;     LDS_WAIT(); asm volatile("" ::: "memory");
; }
	ds_write2_b32 v24, v92, v93 offset1:1
	ds_write2_b32 v25, v94, v95 offset1:1
	s_waitcnt vmcnt(1)
	ds_write2_b32 v26, v96, v97 offset1:1
	ds_write2_b32 v27, v98, v99 offset1:1
	s_waitcnt vmcnt(0)
	ds_write2_b32 v28, v100, v101 offset1:1
	ds_write2_b32 v29, v102, v103 offset1:1
	s_waitcnt lgkmcnt(0)
	ds_read2_b32 v[72:73], v14 offset0:33 offset1:41
	ds_read2_b32 v[76:77], v14 offset1:8
	ds_read2_b32 v[78:79], v14 offset0:66 offset1:74
	ds_read2_b32 v[80:81], v14 offset0:99 offset1:107
	ds_read2_b32 v[82:83], v14 offset0:132 offset1:140
	ds_read2_b32 v[84:85], v14 offset0:165 offset1:173
	ds_read2_b32 v[86:87], v14 offset0:198 offset1:206
	ds_read2_b32 v[88:89], v14 offset0:231 offset1:239
	ds_read2_b32 v[90:91], v14 offset0:49 offset1:57
	ds_read2_b32 v[92:93], v14 offset0:16 offset1:24
	ds_read2_b32 v[94:95], v14 offset0:82 offset1:90
	ds_read2_b32 v[96:97], v14 offset0:115 offset1:123
	ds_read2_b32 v[98:99], v14 offset0:148 offset1:156
	ds_read2_b32 v[100:101], v14 offset0:181 offset1:189
	s_waitcnt lgkmcnt(12)
	v_cvt_pk_bf16_f32 v70, v76, v72
	s_waitcnt lgkmcnt(10)
	v_cvt_pk_bf16_f32 v71, v78, v80
	v_cvt_pk_bf16_f32 v76, v77, v73
	s_waitcnt lgkmcnt(8)
	v_cvt_pk_bf16_f32 v72, v82, v84
	s_waitcnt lgkmcnt(6)
	v_cvt_pk_bf16_f32 v73, v86, v88
	global_store_dwordx4 v[104:105], v[70:73], off sc1
	v_cvt_pk_bf16_f32 v77, v79, v81
	v_cvt_pk_bf16_f32 v78, v83, v85
	ds_read2_b32 v[80:81], v14 offset0:214 offset1:222
	ds_read2_b32 v[82:83], v14 offset0:247 offset1:255
	v_cvt_pk_bf16_f32 v79, v87, v89
	global_store_dwordx4 v[106:107], v[76:79], off sc1
	s_waitcnt lgkmcnt(6)
	v_cvt_pk_bf16_f32 v70, v92, v90
	s_waitcnt lgkmcnt(4)
	v_cvt_pk_bf16_f32 v71, v94, v96
	v_or_b32_e32 v76, s100, v6
	v_ashrrev_i32_e32 v77, 31, v76
	v_lshlrev_b64 v[76:77], 11, v[76:77]
	s_waitcnt lgkmcnt(2)
	v_cvt_pk_bf16_f32 v72, v98, v100
	s_waitcnt lgkmcnt(0)
	v_cvt_pk_bf16_f32 v73, v80, v82
	v_lshl_add_u64 v[76:77], v[108:109], 0, v[76:77]
	global_store_dwordx4 v[76:77], v[70:73], off sc1
	v_or_b32_e32 v76, s100, v7
	v_ashrrev_i32_e32 v77, 31, v76
	v_lshlrev_b64 v[76:77], 11, v[76:77]
	v_cvt_pk_bf16_f32 v70, v93, v91
	v_cvt_pk_bf16_f32 v71, v95, v97
	v_cvt_pk_bf16_f32 v72, v99, v101
	v_cvt_pk_bf16_f32 v73, v81, v83
	v_lshl_add_u64 v[76:77], v[108:109], 0, v[76:77]
	global_store_dwordx4 v[76:77], v[70:73], off sc1
	s_waitcnt lgkmcnt(0)
	s_branch .LBB0_43
.Lw0_single:
	s_waitcnt vmcnt(7)
	ds_write2_b32 v15, v30, v31 offset1:1
	ds_write2_b32 v15, v32, v33 offset0:2 offset1:3
	s_waitcnt vmcnt(6)
	ds_write2_b32 v16, v36, v37 offset1:1
	ds_write2_b32 v17, v38, v39 offset1:1
	s_waitcnt vmcnt(5)
	ds_write2_b32 v18, v40, v41 offset1:1
	ds_write2_b32 v19, v42, v43 offset1:1
	s_waitcnt vmcnt(4)
	ds_write2_b32 v20, v44, v45 offset1:1
	ds_write2_b32 v21, v46, v47 offset1:1
	s_waitcnt vmcnt(3)
	ds_write2_b32 v22, v48, v49 offset1:1
	ds_write2_b32 v23, v50, v51 offset1:1
	s_waitcnt vmcnt(2)
	ds_write2_b32 v24, v52, v53 offset1:1
	ds_write2_b32 v25, v54, v55 offset1:1
	s_waitcnt vmcnt(1)
	ds_write2_b32 v26, v56, v57 offset1:1
	ds_write2_b32 v27, v58, v59 offset1:1
	s_waitcnt vmcnt(0)
	ds_write2_b32 v28, v60, v61 offset1:1
	ds_write2_b32 v29, v62, v63 offset1:1
	s_waitcnt lgkmcnt(0)
	ds_read2_b32 v[32:33], v14 offset0:33 offset1:41
	ds_read2_b32 v[36:37], v14 offset1:8
	ds_read2_b32 v[38:39], v14 offset0:66 offset1:74
	ds_read2_b32 v[40:41], v14 offset0:99 offset1:107
	ds_read2_b32 v[42:43], v14 offset0:132 offset1:140
	ds_read2_b32 v[44:45], v14 offset0:165 offset1:173
	ds_read2_b32 v[46:47], v14 offset0:198 offset1:206
	ds_read2_b32 v[48:49], v14 offset0:231 offset1:239
	ds_read2_b32 v[50:51], v14 offset0:49 offset1:57
	ds_read2_b32 v[52:53], v14 offset0:16 offset1:24
	ds_read2_b32 v[54:55], v14 offset0:82 offset1:90
	ds_read2_b32 v[56:57], v14 offset0:115 offset1:123
	ds_read2_b32 v[58:59], v14 offset0:148 offset1:156
	ds_read2_b32 v[60:61], v14 offset0:181 offset1:189
	s_waitcnt lgkmcnt(12)
	v_cvt_pk_bf16_f32 v30, v36, v32
	s_waitcnt lgkmcnt(10)
	v_cvt_pk_bf16_f32 v31, v38, v40
	v_cvt_pk_bf16_f32 v36, v37, v33
	s_waitcnt lgkmcnt(8)
	v_cvt_pk_bf16_f32 v32, v42, v44
	s_waitcnt lgkmcnt(6)
	v_cvt_pk_bf16_f32 v33, v46, v48
	global_store_dwordx4 v[64:65], v[30:33], off sc1
	v_cvt_pk_bf16_f32 v37, v39, v41
	v_cvt_pk_bf16_f32 v38, v43, v45
	ds_read2_b32 v[40:41], v14 offset0:214 offset1:222
	ds_read2_b32 v[42:43], v14 offset0:247 offset1:255
	v_cvt_pk_bf16_f32 v39, v47, v49
	global_store_dwordx4 v[66:67], v[36:39], off sc1
	s_waitcnt lgkmcnt(6)
	v_cvt_pk_bf16_f32 v30, v52, v50
	s_waitcnt lgkmcnt(4)
	v_cvt_pk_bf16_f32 v31, v54, v56
	v_or_b32_e32 v36, s35, v6
	v_ashrrev_i32_e32 v37, 31, v36
	v_lshlrev_b64 v[36:37], 11, v[36:37]
	s_waitcnt lgkmcnt(2)
	v_cvt_pk_bf16_f32 v32, v58, v60
	s_waitcnt lgkmcnt(0)
	v_cvt_pk_bf16_f32 v33, v40, v42
	v_lshl_add_u64 v[36:37], v[68:69], 0, v[36:37]
	global_store_dwordx4 v[36:37], v[30:33], off sc1
	v_or_b32_e32 v36, s35, v7
	v_ashrrev_i32_e32 v37, 31, v36
	v_lshlrev_b64 v[36:37], 11, v[36:37]
	v_cvt_pk_bf16_f32 v30, v53, v51
	v_cvt_pk_bf16_f32 v31, v55, v57
	v_cvt_pk_bf16_f32 v32, v59, v61
	v_cvt_pk_bf16_f32 v33, v41, v43
	v_lshl_add_u64 v[36:37], v[68:69], 0, v[36:37]
	global_store_dwordx4 v[36:37], v[30:33], off sc1
	s_waitcnt lgkmcnt(0)
